# xstream_counted_waits
# speedup vs baseline: 1.0518x; 1.0045x over previous
; __device__ __forceinline__ void p0_load4(const Args& a, int m0, int NGW, int lane, f32x4 (&v)[4][4]) {
; #pragma unroll
;     for (int u = 0; u < 4; ++u) { const int m = min(m0 + u * NGW, T - 1);
;         const float* xrow = m < TP ? a.in[0] + (size_t)m * 1024 : a.in[1] + (size_t)(m - TP) * 1024;
;         const f32x4* xr = (const f32x4*)xrow + lane;
; #pragma unroll
;         for (int j = 0; j < 4; ++j) v[u][j] = xr[64 * j]; }
; }
; __device__ __forceinline__ void p0_prologue(const Args& a, LAS unsigned char* lds, int wave, int lane) {
;     ...
;         while (m0 < T) {
;             const int m1 = m0 + 4 * NGW; const bool has1 = m1 < T;
;             if (has1) p0_load4(a, m1, NGW, lane, vb);
;             p0_proc4(XB, m0, NGW, lane, va);
;             if (!has1) break;
;             const int m2 = m1 + 4 * NGW; const bool has2 = m2 < T;
;             if (has2) p0_load4(a, m2, NGW, lane, va);
;             p0_proc4(XB, m1, NGW, lane, vb);
;             if (!has2) break;
;             m0 = m2;
;         }
.LBB0_26:
	s_add_i32 s0, s12, s26
	s_add_i32 s10, s0, -6
	s_cmp_gt_i32 s10, 0x3fff
	s_mov_b64 s[0:1], -1
	s_cbranch_scc1 .LBB0_25
	s_add_i32 s0, s20, s26
	s_add_i32 s6, s0, -6
	s_cmp_lt_i32 s6, 0x4000
	s_cselect_b64 s[8:9], -1, 0
	s_cmp_gt_i32 s6, 0x3fff
	s_cbranch_scc1 .LBB0_29
	s_add_i32 s0, s0, 0xffff7ffa
	s_ashr_i32 s1, s6, 31
	s_cmp_lt_i32 s6, 0x8000
	s_cselect_b32 s1, s1, 0
	s_cselect_b32 s0, s6, s0
	s_cselect_b32 s7, s77, s79
	s_cselect_b32 s11, s76, s78
	s_lshl_b64 s[0:1], s[0:1], 12
	s_add_u32 s0, s11, s0
	s_addc_u32 s1, s7, s1
	global_load_dwordx4 v[76:79], v130, s[0:1]
	global_load_dwordx4 v[72:75], v130, s[0:1] offset:1024
	global_load_dwordx4 v[68:71], v130, s[0:1] offset:2048
	global_load_dwordx4 v[64:67], v130, s[0:1] offset:3072
	s_add_i32 s0, s15, s26
	s_min_i32 s7, s0, 0x3fff
	s_ashr_i32 s1, s7, 31
	s_add_i32 s11, s7, 0xffff8000
	s_cmp_lt_i32 s0, 0x8000
	s_cselect_b32 s1, s1, 0
	s_cselect_b32 s0, s7, s11
	s_cselect_b32 s7, s77, s79
	s_cselect_b32 s11, s76, s78
	s_lshl_b64 s[0:1], s[0:1], 12
	s_add_u32 s0, s11, s0
	s_addc_u32 s1, s7, s1
	global_load_dwordx4 v[92:95], v130, s[0:1]
	global_load_dwordx4 v[88:91], v130, s[0:1] offset:1024
	global_load_dwordx4 v[84:87], v130, s[0:1] offset:2048
	global_load_dwordx4 v[80:83], v130, s[0:1] offset:3072
	s_add_i32 s0, s21, s26
	s_min_i32 s7, s0, 0x3fff
	s_ashr_i32 s1, s7, 31
	s_add_i32 s11, s7, 0xffff8000
	s_cmp_lt_i32 s0, 0x8000
	s_cselect_b32 s1, s1, 0
	s_cselect_b32 s0, s7, s11
	s_cselect_b32 s7, s77, s79
	s_cselect_b32 s11, s76, s78
	s_lshl_b64 s[0:1], s[0:1], 12
	s_add_u32 s0, s11, s0
	s_addc_u32 s1, s7, s1
	global_load_dwordx4 v[108:111], v130, s[0:1]
	global_load_dwordx4 v[104:107], v130, s[0:1] offset:1024
	global_load_dwordx4 v[100:103], v130, s[0:1] offset:2048
	global_load_dwordx4 v[96:99], v130, s[0:1] offset:3072
	s_add_i32 s0, s22, s26
	s_min_i32 s7, s0, 0x3fff
	s_ashr_i32 s1, s7, 31
	s_add_i32 s11, s7, 0xffff8000
	s_cmp_lt_i32 s0, 0x8000
	s_cselect_b32 s1, s1, 0
	s_cselect_b32 s0, s7, s11
	s_cselect_b32 s7, s77, s79
	s_cselect_b32 s11, s76, s78
	s_lshl_b64 s[0:1], s[0:1], 12
	s_add_u32 s0, s11, s0
	s_addc_u32 s1, s7, s1
	global_load_dwordx4 v[124:127], v130, s[0:1]
	global_load_dwordx4 v[120:123], v130, s[0:1] offset:1024
	global_load_dwordx4 v[116:119], v130, s[0:1] offset:2048
	global_load_dwordx4 v[112:115], v130, s[0:1] offset:3072
	s_waitcnt vmcnt(16) lgkmcnt(0)
	v_pk_mul_f32 v[134:135], v[2:3], v[2:3]
	v_pk_mul_f32 v[136:137], v[0:1], v[0:1]
	s_branch .Lxs_29go

; __device__ __forceinline__ void p0_proc4(bf16_t* XB, int m0, int NGW, int lane, const f32x4 (&v)[4][4]) {
;     float s[4];
; #pragma unroll
;     for (int u = 0; u < 4; ++u) { float t = 0.f;
; #pragma unroll
;         for (int j = 0; j < 4; ++j) t += (v[u][j][0] * v[u][j][0] + v[u][j][1] * v[u][j][1]) + (v[u][j][2] * v[u][j][2] + v[u][j][3] * v[u][j][3]);
;         s[u] = t; }
; #pragma unroll
;     for (int o = 1; o < 64; o <<= 1) {
; #pragma unroll
;         for (int u = 0; u < 4; ++u) s[u] += __shfl_xor(s[u], o); }
.Lxs_29go:
	v_mul_f32_e32 v142, v63, v63
	v_pk_mov_b32 v[138:139], v[136:137], v[134:135] op_sel:[1,0]
	v_mov_b32_e32 v137, v135
	v_pk_add_f32 v[134:135], v[138:139], v[136:137]
	v_pk_mul_f32 v[136:137], v[6:7], v[6:7]
	v_pk_add_f32 v[134:135], v[134:135], v[134:135] op_sel_hi:[0,1]
	v_pk_mul_f32 v[138:139], v[4:5], v[4:5]
	v_mul_f32_e32 v134, v8, v8
	v_pk_mov_b32 v[140:141], v[138:139], v[136:137] op_sel:[1,0]
	v_mov_b32_e32 v139, v137
	v_pk_add_f32 v[136:137], v[140:141], v[138:139]
	v_pk_fma_f32 v[138:139], v[8:9], v[8:9], v[134:135] op_sel_hi:[1,1,0]
	v_mul_f32_e32 v134, v10, v10
	v_pk_add_f32 v[136:137], v[136:137], v[136:137] op_sel_hi:[0,1]
	v_pk_fma_f32 v[140:141], v[10:11], v[10:11], v[134:135] op_sel_hi:[1,1,0]
	v_mul_f32_e32 v138, v12, v12
	v_mul_f32_e32 v140, v13, v13
	v_mul_f32_e32 v136, v14, v14
	v_mul_f32_e32 v134, v15, v15
	v_pk_add_f32 v[138:139], v[138:139], v[140:141]
	v_pk_add_f32 v[134:135], v[136:137], v[134:135]
	v_mul_f32_e32 v136, v19, v19
	v_pk_add_f32 v[134:135], v[138:139], v[134:135]
	v_fmac_f32_e32 v136, v18, v18
	v_add_f32_e32 v134, v134, v135
	v_mul_f32_e32 v135, v17, v17
	v_fmac_f32_e32 v135, v16, v16
	v_add_f32_e32 v135, v135, v136
	v_mul_f32_e32 v136, v21, v21
	v_mul_f32_e32 v137, v23, v23
	v_fmac_f32_e32 v136, v20, v20
	v_fmac_f32_e32 v137, v22, v22
	v_add_f32_e32 v136, v136, v137
	v_add_f32_e32 v135, v136, v135
	v_mul_f32_e32 v136, v25, v25
	v_mul_f32_e32 v137, v27, v27
	v_fmac_f32_e32 v136, v24, v24
	v_fmac_f32_e32 v137, v26, v26
	v_add_f32_e32 v136, v136, v137
	v_add_f32_e32 v135, v136, v135
	v_mul_f32_e32 v136, v29, v29
	v_mul_f32_e32 v137, v31, v31
	v_fmac_f32_e32 v136, v28, v28
	v_fmac_f32_e32 v137, v30, v30
	v_add_f32_e32 v136, v136, v137
	v_add_f32_e32 v137, v136, v135
	v_mul_f32_e32 v135, v33, v33
	v_mul_f32_e32 v136, v35, v35
	v_fmac_f32_e32 v135, v32, v32
	v_fmac_f32_e32 v136, v34, v34
	v_add_f32_e32 v135, v135, v136
	v_mul_f32_e32 v136, v37, v37
	v_mul_f32_e32 v138, v39, v39
	v_fmac_f32_e32 v136, v36, v36
	v_fmac_f32_e32 v138, v38, v38
	v_add_f32_e32 v136, v136, v138
	v_add_f32_e32 v135, v136, v135
	v_mul_f32_e32 v136, v41, v41
	v_mul_f32_e32 v138, v43, v43
	v_fmac_f32_e32 v136, v40, v40
	v_fmac_f32_e32 v138, v42, v42
	v_add_f32_e32 v136, v136, v138
	v_add_f32_e32 v135, v136, v135
	v_mul_f32_e32 v136, v45, v45
	v_mul_f32_e32 v138, v47, v47
	v_fmac_f32_e32 v136, v44, v44
	v_fmac_f32_e32 v138, v46, v46
	v_add_f32_e32 v136, v136, v138
	v_add_f32_e32 v138, v136, v135
	v_mul_f32_e32 v135, v49, v49
	v_mul_f32_e32 v136, v51, v51
	v_fmac_f32_e32 v135, v48, v48
	v_fmac_f32_e32 v136, v50, v50
	v_add_f32_e32 v135, v135, v136
	v_mul_f32_e32 v136, v53, v53
	v_mul_f32_e32 v139, v55, v55
	v_fmac_f32_e32 v136, v52, v52
	v_fmac_f32_e32 v139, v54, v54
	v_add_f32_e32 v136, v136, v139
	v_add_f32_e32 v135, v136, v135
	v_mul_f32_e32 v136, v57, v57
	v_mul_f32_e32 v139, v59, v59
	v_fmac_f32_e32 v136, v56, v56
	v_fmac_f32_e32 v139, v58, v58
	v_add_f32_e32 v136, v136, v139
	v_add_f32_e32 v139, v136, v135
	v_and_b32_e32 v135, 64, v133
	v_add_u32_e32 v140, 64, v135
	v_xor_b32_e32 v135, 1, v133
	v_cmp_lt_i32_e32 vcc, v135, v140
	v_mul_f32_e32 v136, v61, v61
	v_fmac_f32_e32 v136, v60, v60
	v_cndmask_b32_e32 v135, v133, v135, vcc
	v_lshlrev_b32_e32 v135, 2, v135
	ds_bpermute_b32 v141, v135, v134
	v_fmac_f32_e32 v142, v62, v62
	v_add_f32_e32 v142, v136, v142
	v_xor_b32_e32 v136, 2, v133
	v_cmp_lt_i32_e32 vcc, v136, v140
	s_waitcnt lgkmcnt(0)
	v_add_f32_e32 v134, v134, v141
	ds_bpermute_b32 v141, v135, v137
	v_cndmask_b32_e32 v136, v133, v136, vcc
	ds_bpermute_b32 v143, v135, v138
	v_lshlrev_b32_e32 v136, 2, v136
	ds_bpermute_b32 v144, v136, v134
	v_add_f32_e32 v139, v142, v139
	s_waitcnt lgkmcnt(2)
	v_add_f32_e32 v141, v137, v141
	s_waitcnt lgkmcnt(1)
	v_add_f32_e32 v138, v138, v143
	v_xor_b32_e32 v137, 4, v133
	ds_bpermute_b32 v142, v135, v139
	s_waitcnt lgkmcnt(1)
	v_add_f32_e32 v134, v134, v144
	ds_bpermute_b32 v144, v136, v138
	v_cmp_lt_i32_e32 vcc, v137, v140
	ds_bpermute_b32 v143, v136, v141
	s_waitcnt lgkmcnt(2)
	v_add_f32_e32 v139, v139, v142
	v_cndmask_b32_e32 v137, v133, v137, vcc
	v_lshlrev_b32_e32 v137, 2, v137
	ds_bpermute_b32 v145, v137, v134
	s_waitcnt lgkmcnt(2)
	v_add_f32_e32 v142, v138, v144
	v_xor_b32_e32 v138, 8, v133
	s_waitcnt lgkmcnt(1)
	v_add_f32_e32 v141, v141, v143
	ds_bpermute_b32 v143, v136, v139
	v_cmp_lt_i32_e32 vcc, v138, v140
	s_waitcnt lgkmcnt(1)
	v_add_f32_e32 v134, v134, v145
	ds_bpermute_b32 v144, v137, v141
	v_cndmask_b32_e32 v138, v133, v138, vcc
	v_lshlrev_b32_e32 v138, 2, v138
	ds_bpermute_b32 v146, v138, v134
	ds_bpermute_b32 v145, v137, v142
	s_waitcnt lgkmcnt(3)
	v_add_f32_e32 v143, v139, v143
	v_xor_b32_e32 v139, 16, v133
	v_cmp_lt_i32_e32 vcc, v139, v140
	s_waitcnt lgkmcnt(2)
	v_add_f32_e32 v141, v141, v144
	s_waitcnt lgkmcnt(1)
	v_add_f32_e32 v134, v134, v146
	v_cndmask_b32_e32 v139, v133, v139, vcc
	v_lshlrev_b32_e32 v139, 2, v139
	s_waitcnt lgkmcnt(0)
	v_add_f32_e32 v142, v142, v145
	ds_bpermute_b32 v145, v138, v141
	ds_bpermute_b32 v147, v139, v134
	ds_bpermute_b32 v144, v137, v143
	ds_bpermute_b32 v146, v138, v142
	s_ashr_i32 s11, s10, 31
	s_waitcnt lgkmcnt(3)
	v_add_f32_e32 v141, v141, v145
	s_waitcnt lgkmcnt(2)
	v_add_f32_e32 v145, v134, v147
	v_xor_b32_e32 v134, 32, v133
	v_cmp_lt_i32_e32 vcc, v134, v140
	s_waitcnt lgkmcnt(1)
	v_add_f32_e32 v143, v143, v144
	ds_bpermute_b32 v144, v138, v143
	v_cndmask_b32_e32 v134, v133, v134, vcc
	v_lshlrev_b32_e32 v134, 2, v134
	ds_bpermute_b32 v140, v134, v145
	s_waitcnt lgkmcnt(2)
	v_add_f32_e32 v142, v142, v146
	s_waitcnt lgkmcnt(1)
	v_add_f32_e32 v143, v143, v144
	ds_bpermute_b32 v144, v139, v141
	ds_bpermute_b32 v147, v139, v143
	s_waitcnt lgkmcnt(2)
; __device__ __forceinline__ unsigned cvt_pk_bf16(float lo, float hi) { const f32x2_t v = {lo, hi}; const bf16x2_t r = __builtin_convertvector(v, bf16x2_t); return __builtin_bit_cast(unsigned, r); }
; __device__ __forceinline__ void p0_proc4(bf16_t* XB, int m0, int NGW, int lane, const f32x4 (&v)[4][4]) {
;     ...
; #pragma unroll
;     for (int u = 0; u < 4; ++u) { const int m = m0 + u * NGW; if (m >= T) break;
;         const float rstd = 1.0f / sqrtf(s[u] * (1.0f / 1024.0f) + NORM_EPS);
;         u32x2* o8 = (u32x2*)(XB + (size_t)m * 1024) + lane;
; #pragma unroll
;         for (int j = 0; j < 4; ++j) { u32x2 w; w.x = cvt_pk_bf16(v[u][j][0] * rstd, v[u][j][1] * rstd); w.y = cvt_pk_bf16(v[u][j][2] * rstd, v[u][j][3] * rstd); o8[64 * j] = w; } }
	v_add_f32_e32 v140, v145, v140
	v_fmamk_f32 v140, v140, 0x3a800000, v131
	v_mul_f32_e32 v145, 0x4f800000, v140
	v_cmp_gt_f32_e32 vcc, s25, v140
	ds_bpermute_b32 v146, v139, v142
	s_waitcnt lgkmcnt(2)
	v_add_f32_e32 v144, v141, v144
	v_cndmask_b32_e32 v145, v140, v145, vcc
	v_sqrt_f32_e32 v148, v145
	s_waitcnt lgkmcnt(1)
	v_add_f32_e32 v140, v143, v147
	s_waitcnt lgkmcnt(0)
	v_add_f32_e32 v142, v142, v146
	v_add_u32_e32 v141, -1, v148
	v_fma_f32 v143, -v141, v148, v145
	v_cmp_ge_f32_e64 s[0:1], 0, v143
	v_add_u32_e32 v143, 1, v148
	v_fma_f32 v146, -v143, v148, v145
	v_cndmask_b32_e64 v141, v148, v141, s[0:1]
	v_cmp_lt_f32_e64 s[0:1], 0, v146
	s_nop 1
	v_cndmask_b32_e64 v141, v141, v143, s[0:1]
	v_mul_f32_e32 v143, 0x37800000, v141
	v_cndmask_b32_e32 v141, v141, v143, vcc
	v_cmp_class_f32_e32 vcc, v145, v132
	ds_bpermute_b32 v143, v134, v142
	s_nop 0
	v_cndmask_b32_e32 v146, v141, v145, vcc
	v_div_scale_f32 v147, s[0:1], v146, v146, 1.0
	v_rcp_f32_e32 v148, v147
	s_lshl_b64 s[0:1], s[10:11], 11
	ds_bpermute_b32 v145, v134, v144
	ds_bpermute_b32 v141, v134, v140
	v_fma_f32 v149, -v147, v148, 1.0
	v_fmac_f32_e32 v148, v149, v148
	v_div_scale_f32 v149, vcc, 1.0, v146, 1.0
	v_mul_f32_e32 v150, v149, v148
	v_fma_f32 v151, -v147, v150, v149
	v_fmac_f32_e32 v150, v151, v148
	v_fma_f32 v147, -v147, v150, v149
	v_div_fmas_f32 v147, v147, v148, v150
	v_div_fixup_f32 v146, v147, v146, 1.0
	v_pk_mul_f32 v[150:151], v[0:1], v[146:147] op_sel_hi:[1,0]
	v_pk_mul_f32 v[152:153], v[2:3], v[146:147] op_sel_hi:[1,0]
	v_lshl_add_u64 v[148:149], v[128:129], 0, s[0:1]
	v_cvt_pk_bf16_f32 v150, v150, v151
	v_cvt_pk_bf16_f32 v151, v152, v153
	global_store_dwordx2 v[148:149], v[150:151], off
	v_pk_mul_f32 v[150:151], v[4:5], v[146:147] op_sel_hi:[1,0]
	v_pk_mul_f32 v[152:153], v[6:7], v[146:147] op_sel_hi:[1,0]
	v_cvt_pk_bf16_f32 v150, v150, v151
	v_cvt_pk_bf16_f32 v151, v152, v153
	global_store_dwordx2 v[148:149], v[150:151], off offset:512
	v_pk_mul_f32 v[150:151], v[8:9], v[146:147] op_sel_hi:[1,0]
	v_pk_mul_f32 v[152:153], v[10:11], v[146:147] op_sel_hi:[1,0]
	v_cvt_pk_bf16_f32 v150, v150, v151
	v_cvt_pk_bf16_f32 v151, v152, v153
	global_store_dwordx2 v[148:149], v[150:151], off offset:1024
	v_pk_mul_f32 v[150:151], v[12:13], v[146:147] op_sel_hi:[1,0]
	v_pk_mul_f32 v[146:147], v[14:15], v[146:147] op_sel_hi:[1,0]
	s_add_i32 s10, s13, s26
	v_cvt_pk_bf16_f32 v150, v150, v151
	v_cvt_pk_bf16_f32 v151, v146, v147
	s_cmp_gt_i32 s10, 0x3fff
	global_store_dwordx2 v[148:149], v[150:151], off offset:1536
	s_cbranch_scc1 .LBB0_33
	s_waitcnt lgkmcnt(1)
	v_add_f32_e32 v144, v144, v145
	v_fmamk_f32 v144, v144, 0x3a800000, v131
	v_mul_f32_e32 v145, 0x4f800000, v144
	v_cmp_gt_f32_e32 vcc, s25, v144
	s_ashr_i32 s11, s10, 31
	s_nop 0
	v_cndmask_b32_e32 v144, v144, v145, vcc
	v_sqrt_f32_e32 v145, v144
	s_nop 0
	v_add_u32_e32 v146, -1, v145
	v_fma_f32 v148, -v146, v145, v144
	v_add_u32_e32 v147, 1, v145
	v_cmp_ge_f32_e64 s[0:1], 0, v148
	s_nop 1
	v_cndmask_b32_e64 v146, v145, v146, s[0:1]
	v_fma_f32 v145, -v147, v145, v144
	v_cmp_lt_f32_e64 s[0:1], 0, v145
	s_nop 1
	v_cndmask_b32_e64 v145, v146, v147, s[0:1]
	v_mul_f32_e32 v146, 0x37800000, v145
	v_cndmask_b32_e32 v145, v145, v146, vcc
	v_cmp_class_f32_e32 vcc, v144, v132
	s_nop 1
	v_cndmask_b32_e32 v144, v145, v144, vcc
	v_div_scale_f32 v145, s[0:1], v144, v144, 1.0
	v_rcp_f32_e32 v146, v145
	s_lshl_b64 s[0:1], s[10:11], 11
	s_add_i32 s10, s23, s26
	s_cmp_gt_i32 s10, 0x3fff
	v_fma_f32 v147, -v145, v146, 1.0
	v_fmac_f32_e32 v146, v147, v146
	v_div_scale_f32 v147, vcc, 1.0, v144, 1.0
	v_mul_f32_e32 v148, v147, v146
	v_fma_f32 v149, -v145, v148, v147
	v_fmac_f32_e32 v148, v149, v146
	v_fma_f32 v145, -v145, v148, v147
	v_div_fmas_f32 v145, v145, v146, v148
	v_div_fixup_f32 v144, v145, v144, 1.0
	v_pk_mul_f32 v[148:149], v[16:17], v[144:145] op_sel_hi:[1,0]
	v_pk_mul_f32 v[150:151], v[18:19], v[144:145] op_sel_hi:[1,0]
	v_lshl_add_u64 v[146:147], v[128:129], 0, s[0:1]
	v_cvt_pk_bf16_f32 v148, v148, v149
	v_cvt_pk_bf16_f32 v149, v150, v151
	global_store_dwordx2 v[146:147], v[148:149], off
	v_pk_mul_f32 v[148:149], v[20:21], v[144:145] op_sel_hi:[1,0]
	v_pk_mul_f32 v[150:151], v[22:23], v[144:145] op_sel_hi:[1,0]
	v_cvt_pk_bf16_f32 v148, v148, v149
	v_cvt_pk_bf16_f32 v149, v150, v151
	global_store_dwordx2 v[146:147], v[148:149], off offset:512
	v_pk_mul_f32 v[148:149], v[24:25], v[144:145] op_sel_hi:[1,0]
	v_pk_mul_f32 v[150:151], v[26:27], v[144:145] op_sel_hi:[1,0]
	v_cvt_pk_bf16_f32 v148, v148, v149
	v_cvt_pk_bf16_f32 v149, v150, v151
	global_store_dwordx2 v[146:147], v[148:149], off offset:1024
	v_pk_mul_f32 v[148:149], v[28:29], v[144:145] op_sel_hi:[1,0]
	v_pk_mul_f32 v[144:145], v[30:31], v[144:145] op_sel_hi:[1,0]
	v_cvt_pk_bf16_f32 v148, v148, v149
	v_cvt_pk_bf16_f32 v149, v144, v145
	global_store_dwordx2 v[146:147], v[148:149], off offset:1536
	s_cbranch_scc1 .LBB0_33
; __device__ __forceinline__ unsigned cvt_pk_bf16(float lo, float hi) { const f32x2_t v = {lo, hi}; const bf16x2_t r = __builtin_convertvector(v, bf16x2_t); return __builtin_bit_cast(unsigned, r); }
; __device__ __forceinline__ void p0_proc4(bf16_t* XB, int m0, int NGW, int lane, const f32x4 (&v)[4][4]) {
;     ...
; #pragma unroll
;     for (int u = 0; u < 4; ++u) { const int m = m0 + u * NGW; if (m >= T) break;
;         const float rstd = 1.0f / sqrtf(s[u] * (1.0f / 1024.0f) + NORM_EPS);
;         u32x2* o8 = (u32x2*)(XB + (size_t)m * 1024) + lane;
; #pragma unroll
;         for (int j = 0; j < 4; ++j) { u32x2 w; w.x = cvt_pk_bf16(v[u][j][0] * rstd, v[u][j][1] * rstd); w.y = cvt_pk_bf16(v[u][j][2] * rstd, v[u][j][3] * rstd); o8[64 * j] = w; } }
; __device__ __forceinline__ void p0_prologue(const Args& a, LAS unsigned char* lds, int wave, int lane) {
;     ...
;         while (m0 < T) {
;             const int m1 = m0 + 4 * NGW; const bool has1 = m1 < T;
;             if (has1) p0_load4(a, m1, NGW, lane, vb);
;             p0_proc4(XB, m0, NGW, lane, va);
;             if (!has1) break;
;             const int m2 = m1 + 4 * NGW; const bool has2 = m2 < T;
;             if (has2) p0_load4(a, m2, NGW, lane, va);
;             p0_proc4(XB, m1, NGW, lane, vb);
;             if (!has2) break;
;             m0 = m2;
;         }
	v_add_f32_e32 v142, v142, v143
	v_fmamk_f32 v142, v142, 0x3a800000, v131
	v_mul_f32_e32 v143, 0x4f800000, v142
	v_cmp_gt_f32_e32 vcc, s25, v142
	s_ashr_i32 s11, s10, 31
	s_nop 0
	v_cndmask_b32_e32 v142, v142, v143, vcc
	v_sqrt_f32_e32 v143, v142
	s_nop 0
	v_add_u32_e32 v144, -1, v143
	v_fma_f32 v146, -v144, v143, v142
	v_add_u32_e32 v145, 1, v143
	v_cmp_ge_f32_e64 s[0:1], 0, v146
	s_nop 1
	v_cndmask_b32_e64 v144, v143, v144, s[0:1]
	v_fma_f32 v143, -v145, v143, v142
	v_cmp_lt_f32_e64 s[0:1], 0, v143
	s_nop 1
	v_cndmask_b32_e64 v143, v144, v145, s[0:1]
	v_mul_f32_e32 v144, 0x37800000, v143
	v_cndmask_b32_e32 v143, v143, v144, vcc
	v_cmp_class_f32_e32 vcc, v142, v132
	s_nop 1
	v_cndmask_b32_e32 v142, v143, v142, vcc
	v_div_scale_f32 v143, s[0:1], v142, v142, 1.0
	v_rcp_f32_e32 v144, v143
	s_lshl_b64 s[0:1], s[10:11], 11
	s_add_i32 s10, s24, s26
	s_cmp_gt_i32 s10, 0x3fff
	v_fma_f32 v145, -v143, v144, 1.0
	v_fmac_f32_e32 v144, v145, v144
	v_div_scale_f32 v145, vcc, 1.0, v142, 1.0
	v_mul_f32_e32 v146, v145, v144
	v_fma_f32 v147, -v143, v146, v145
	v_fmac_f32_e32 v146, v147, v144
	v_fma_f32 v143, -v143, v146, v145
	v_div_fmas_f32 v143, v143, v144, v146
	v_div_fixup_f32 v142, v143, v142, 1.0
	v_pk_mul_f32 v[146:147], v[32:33], v[142:143] op_sel_hi:[1,0]
	v_pk_mul_f32 v[148:149], v[34:35], v[142:143] op_sel_hi:[1,0]
	v_lshl_add_u64 v[144:145], v[128:129], 0, s[0:1]
	v_cvt_pk_bf16_f32 v146, v146, v147
	v_cvt_pk_bf16_f32 v147, v148, v149
	global_store_dwordx2 v[144:145], v[146:147], off
	v_pk_mul_f32 v[146:147], v[36:37], v[142:143] op_sel_hi:[1,0]
	v_pk_mul_f32 v[148:149], v[38:39], v[142:143] op_sel_hi:[1,0]
	v_cvt_pk_bf16_f32 v146, v146, v147
	v_cvt_pk_bf16_f32 v147, v148, v149
	global_store_dwordx2 v[144:145], v[146:147], off offset:512
	v_pk_mul_f32 v[146:147], v[40:41], v[142:143] op_sel_hi:[1,0]
	v_pk_mul_f32 v[148:149], v[42:43], v[142:143] op_sel_hi:[1,0]
	v_cvt_pk_bf16_f32 v146, v146, v147
	v_cvt_pk_bf16_f32 v147, v148, v149
	global_store_dwordx2 v[144:145], v[146:147], off offset:1024
	v_pk_mul_f32 v[146:147], v[44:45], v[142:143] op_sel_hi:[1,0]
	v_pk_mul_f32 v[142:143], v[46:47], v[142:143] op_sel_hi:[1,0]
	v_cvt_pk_bf16_f32 v146, v146, v147
	v_cvt_pk_bf16_f32 v147, v142, v143
	global_store_dwordx2 v[144:145], v[146:147], off offset:1536
	s_cbranch_scc1 .LBB0_33
	s_waitcnt lgkmcnt(0)
	v_add_f32_e32 v140, v140, v141
	v_fmamk_f32 v140, v140, 0x3a800000, v131
	v_mul_f32_e32 v141, 0x4f800000, v140
	v_cmp_gt_f32_e32 vcc, s25, v140
	s_ashr_i32 s11, s10, 31
	s_nop 0
	v_cndmask_b32_e32 v140, v140, v141, vcc
	v_sqrt_f32_e32 v141, v140
	s_nop 0
	v_add_u32_e32 v142, -1, v141
	v_fma_f32 v144, -v142, v141, v140
	v_add_u32_e32 v143, 1, v141
	v_cmp_ge_f32_e64 s[0:1], 0, v144
	s_nop 1
	v_cndmask_b32_e64 v142, v141, v142, s[0:1]
	v_fma_f32 v141, -v143, v141, v140
	v_cmp_lt_f32_e64 s[0:1], 0, v141
	s_nop 1
	v_cndmask_b32_e64 v141, v142, v143, s[0:1]
	v_mul_f32_e32 v142, 0x37800000, v141
	v_cndmask_b32_e32 v141, v141, v142, vcc
	v_cmp_class_f32_e32 vcc, v140, v132
	s_nop 1
	v_cndmask_b32_e32 v140, v141, v140, vcc
	v_div_scale_f32 v141, s[0:1], v140, v140, 1.0
	v_rcp_f32_e32 v142, v141
	s_lshl_b64 s[0:1], s[10:11], 11
	v_fma_f32 v143, -v141, v142, 1.0
	v_fmac_f32_e32 v142, v143, v142
	v_div_scale_f32 v143, vcc, 1.0, v140, 1.0
	v_mul_f32_e32 v144, v143, v142
	v_fma_f32 v145, -v141, v144, v143
	v_fmac_f32_e32 v144, v145, v142
	v_fma_f32 v141, -v141, v144, v143
	v_div_fmas_f32 v141, v141, v142, v144
	v_div_fixup_f32 v140, v141, v140, 1.0
	v_pk_mul_f32 v[144:145], v[48:49], v[140:141] op_sel_hi:[1,0]
	v_pk_mul_f32 v[146:147], v[50:51], v[140:141] op_sel_hi:[1,0]
	v_lshl_add_u64 v[142:143], v[128:129], 0, s[0:1]
	v_cvt_pk_bf16_f32 v144, v144, v145
	v_cvt_pk_bf16_f32 v145, v146, v147
	global_store_dwordx2 v[142:143], v[144:145], off
	v_pk_mul_f32 v[144:145], v[52:53], v[140:141] op_sel_hi:[1,0]
	v_pk_mul_f32 v[146:147], v[54:55], v[140:141] op_sel_hi:[1,0]
	v_cvt_pk_bf16_f32 v144, v144, v145
	v_cvt_pk_bf16_f32 v145, v146, v147
	global_store_dwordx2 v[142:143], v[144:145], off offset:512
	v_pk_mul_f32 v[144:145], v[56:57], v[140:141] op_sel_hi:[1,0]
	v_pk_mul_f32 v[146:147], v[58:59], v[140:141] op_sel_hi:[1,0]
	v_cvt_pk_bf16_f32 v144, v144, v145
	v_cvt_pk_bf16_f32 v145, v146, v147
	global_store_dwordx2 v[142:143], v[144:145], off offset:1024
	v_pk_mul_f32 v[144:145], v[60:61], v[140:141] op_sel_hi:[1,0]
	v_pk_mul_f32 v[140:141], v[62:63], v[140:141] op_sel_hi:[1,0]
	v_cvt_pk_bf16_f32 v144, v144, v145
	v_cvt_pk_bf16_f32 v145, v140, v141
	global_store_dwordx2 v[142:143], v[144:145], off offset:1536
.LBB0_33:
	s_andn2_b64 vcc, exec, s[8:9]
	s_mov_b64 s[0:1], -1
	s_cbranch_vccnz .LBB0_25
	s_add_i32 s1, s16, s26
	s_add_i32 s0, s1, -6
	s_cmp_gt_i32 s0, 0x3fff
	s_cbranch_scc1 .Lxs_skip36
	s_add_i32 s7, s1, 0xffff7ffa
	s_ashr_i32 s1, s0, 31
	s_cmp_lt_i32 s0, 0x8000
	s_cselect_b32 s1, s1, 0
	s_cselect_b32 s0, s0, s7
	s_cselect_b32 s7, s77, s79
	s_cselect_b32 s8, s76, s78
	s_lshl_b64 s[0:1], s[0:1], 12
	s_add_u32 s0, s8, s0
	s_addc_u32 s1, s7, s1
	global_load_dwordx4 v[0:3], v130, s[0:1]
	global_load_dwordx4 v[4:7], v130, s[0:1] offset:1024
	global_load_dwordx4 v[8:11], v130, s[0:1] offset:2048
	global_load_dwordx4 v[12:15], v130, s[0:1] offset:3072
	s_add_i32 s0, s17, s26
	s_min_i32 s7, s0, 0x3fff
	s_ashr_i32 s1, s7, 31
	s_add_i32 s8, s7, 0xffff8000
	s_cmp_lt_i32 s0, 0x8000
	s_cselect_b32 s1, s1, 0
	s_cselect_b32 s0, s7, s8
	s_cselect_b32 s7, s77, s79
	s_cselect_b32 s8, s76, s78
	s_lshl_b64 s[0:1], s[0:1], 12
	s_add_u32 s0, s8, s0
	s_addc_u32 s1, s7, s1
	global_load_dwordx4 v[16:19], v130, s[0:1]
	global_load_dwordx4 v[20:23], v130, s[0:1] offset:1024
	global_load_dwordx4 v[24:27], v130, s[0:1] offset:2048
	global_load_dwordx4 v[28:31], v130, s[0:1] offset:3072
	s_add_i32 s0, s18, s26
	s_min_i32 s7, s0, 0x3fff
	s_ashr_i32 s1, s7, 31
	s_add_i32 s8, s7, 0xffff8000
	s_cmp_lt_i32 s0, 0x8000
	s_cselect_b32 s1, s1, 0
	s_cselect_b32 s0, s7, s8
	s_cselect_b32 s7, s77, s79
	s_cselect_b32 s8, s76, s78
	s_lshl_b64 s[0:1], s[0:1], 12
	s_add_u32 s0, s8, s0
	s_addc_u32 s1, s7, s1
	global_load_dwordx4 v[32:35], v130, s[0:1]
	global_load_dwordx4 v[36:39], v130, s[0:1] offset:1024
	global_load_dwordx4 v[40:43], v130, s[0:1] offset:2048
	global_load_dwordx4 v[44:47], v130, s[0:1] offset:3072
	s_add_i32 s0, s19, s26
	s_min_i32 s7, s0, 0x3fff
	s_ashr_i32 s1, s7, 31
	s_add_i32 s8, s7, 0xffff8000
	s_cmp_lt_i32 s0, 0x8000
	s_cselect_b32 s1, s1, 0
	s_cselect_b32 s0, s7, s8
	s_cselect_b32 s7, s77, s79
	s_cselect_b32 s8, s76, s78
	s_lshl_b64 s[0:1], s[0:1], 12
	s_add_u32 s0, s8, s0
	s_addc_u32 s1, s7, s1
	global_load_dwordx4 v[48:51], v130, s[0:1]
	global_load_dwordx4 v[52:55], v130, s[0:1] offset:1024
	global_load_dwordx4 v[56:59], v130, s[0:1] offset:2048
	global_load_dwordx4 v[60:63], v130, s[0:1] offset:3072
	s_waitcnt vmcnt(16)

; __device__ __forceinline__ void p0_prologue(const Args& a, LAS unsigned char* lds, int wave, int lane) {
;     ...
;         while (m0 < T) {
;             const int m1 = m0 + 4 * NGW; const bool has1 = m1 < T;
;             if (has1) p0_load4(a, m1, NGW, lane, vb);
;             p0_proc4(XB, m0, NGW, lane, va);
;             if (!has1) break;
;             const int m2 = m1 + 4 * NGW; const bool has2 = m2 < T;
;             if (has2) p0_load4(a, m2, NGW, lane, va);
;             p0_proc4(XB, m1, NGW, lane, vb);
;             if (!has2) break;
;             m0 = m2;
;         }
.Lxs_skip36:
	s_waitcnt vmcnt(0)
	s_branch .LBB0_36

; #define LAS __attribute__((address_space(3)))
; __global__ void __launch_bounds__(512, 2) fwd_kernel(Args a) {
;     ...
;         { float mqa = fabsf(a.in[4][lane]), mka = fabsf(a.in[5][lane]), mqb = fabsf(a.in[7][lane]), mkb = fabsf(a.in[8][lane]), msk = fabsf(a.in[9][lane & 7]), mr = 0.f;
;           for (int i = tid; i < 8 * 465; i += 512) mr = fmaxf(mr, fabsf(a.in[6][i]));
; #pragma unroll
;           for (int o = 1; o < 64; o <<= 1) { mqa = fmaxf(mqa, __shfl_xor(mqa, o)); mka = fmaxf(mka, __shfl_xor(mka, o)); mqb = fmaxf(mqb, __shfl_xor(mqb, o)); mkb = fmaxf(mkb, __shfl_xor(mkb, o));
;               msk = fmaxf(msk, __shfl_xor(msk, o)); mr = fmaxf(mr, __shfl_xor(mr, o)); }
;           LAS float* red = (LAS float*)(lds + ATT_RPB);
;           if (lane == 0) red[wave] = mr;
.LBB0_268:
	s_mov_b64 s[4:5], 0x1000
	v_mov_b32_e32 v17, 0
	global_load_dword v10, v[0:1], off
	global_load_dword v11, v[0:1], off offset:2048
	v_lshl_add_u64 v[20:21], v[0:1], 0, s[4:5]
	global_load_dword v12, v[20:21], off
	global_load_dword v13, v[20:21], off offset:2048
	v_lshl_add_u64 v[22:23], v[20:21], 0, s[4:5]
	global_load_dword v14, v[22:23], off
	global_load_dword v15, v[22:23], off offset:2048
	v_lshl_add_u64 v[24:25], v[22:23], 0, s[4:5]
	global_load_dword v16, v[24:25], off
	v_cmp_gt_u32_e32 vcc, 0x88, v190
	s_and_saveexec_b64 s[0:1], vcc
	global_load_dword v17, v[24:25], off offset:2048
	s_mov_b64 exec, s[0:1]
	s_waitcnt vmcnt(0)
	v_max_f32_e64 v153, |v10|, |v11|
	v_max3_f32 v153, v153, |v12|, |v13|
	v_max3_f32 v153, v153, |v14|, |v15|
	v_max3_f32 v153, v153, |v16|, |v17|
	s_or_b64 exec, exec, s[0:1]
	v_mbcnt_lo_u32_b32 v7, -1, 0
	v_mbcnt_hi_u32_b32 v7, -1, v7
	v_and_b32_e32 v8, 64, v7
	v_add_u32_e32 v8, 64, v8
	v_xor_b32_e32 v9, 1, v7
	v_cmp_lt_i32_e32 vcc, v9, v8
	v_and_b32_e32 v0, 0x7fffffff, v6
	v_and_b32_e32 v1, 0x7fffffff, v5
	v_cndmask_b32_e32 v9, v7, v9, vcc
	v_lshlrev_b32_e32 v9, 2, v9
	ds_bpermute_b32 v0, v9, v0
	ds_bpermute_b32 v1, v9, v1
	v_and_b32_e32 v10, 0x7fffffff, v3
	v_max_f32_e64 v6, |v6|, |v6|
	v_and_b32_e32 v11, 0x7fffffff, v2
	s_waitcnt lgkmcnt(1)
	v_max_f32_e32 v0, v0, v0
	v_max_f32_e32 v0, v6, v0
	ds_bpermute_b32 v6, v9, v10
	s_waitcnt lgkmcnt(1)
	v_max_f32_e32 v1, v1, v1
	v_max_f32_e64 v5, |v5|, |v5|
	v_and_b32_e32 v12, 0x7fffffff, v4
	v_max_f32_e32 v1, v5, v1
	ds_bpermute_b32 v5, v9, v11
	ds_bpermute_b32 v10, v9, v12
	s_waitcnt lgkmcnt(2)
	v_max_f32_e32 v6, v6, v6
	v_max_f32_e64 v3, |v3|, |v3|
	v_max_f32_e32 v3, v3, v6
	v_xor_b32_e32 v6, 2, v7
	v_cmp_lt_i32_e32 vcc, v6, v8
	s_waitcnt lgkmcnt(1)
	v_max_f32_e32 v5, v5, v5
	v_max_f32_e64 v2, |v2|, |v2|
	v_cndmask_b32_e32 v6, v7, v6, vcc
	v_max_f32_e32 v2, v2, v5
	s_waitcnt lgkmcnt(0)
	v_max_f32_e32 v5, v10, v10
	v_max_f32_e64 v4, |v4|, |v4|
	v_lshlrev_b32_e32 v6, 2, v6
	v_max_f32_e32 v4, v4, v5
	ds_bpermute_b32 v5, v9, v153
	ds_bpermute_b32 v9, v6, v0
	ds_bpermute_b32 v11, v6, v1
	v_max_f32_e32 v10, v153, v153
	s_waitcnt lgkmcnt(2)
	v_max_f32_e32 v5, v5, v5
	s_waitcnt lgkmcnt(1)
	v_max_f32_e32 v9, v9, v9
	v_max_f32_e32 v0, v0, v9
	ds_bpermute_b32 v9, v6, v3
	v_max_f32_e32 v5, v10, v5
	s_waitcnt lgkmcnt(1)
	v_max_f32_e32 v10, v11, v11
	ds_bpermute_b32 v11, v6, v2
	v_max_f32_e32 v1, v1, v10
	ds_bpermute_b32 v10, v6, v4
	s_waitcnt lgkmcnt(2)
	v_max_f32_e32 v9, v9, v9
	v_max_f32_e32 v3, v3, v9
	s_waitcnt lgkmcnt(1)
	v_max_f32_e32 v9, v11, v11
	v_max_f32_e32 v2, v2, v9
	s_waitcnt lgkmcnt(0)
	v_max_f32_e32 v9, v10, v10
	v_xor_b32_e32 v10, 4, v7
	v_cmp_lt_i32_e32 vcc, v10, v8
	ds_bpermute_b32 v6, v6, v5
	v_max_f32_e32 v4, v4, v9
	v_cndmask_b32_e32 v10, v7, v10, vcc
	v_lshlrev_b32_e32 v10, 2, v10
	ds_bpermute_b32 v11, v10, v0
	ds_bpermute_b32 v9, v10, v1
	s_waitcnt lgkmcnt(2)
	v_max_f32_e32 v6, v6, v6
	v_max_f32_e32 v5, v5, v6
	s_waitcnt lgkmcnt(1)
	v_max_f32_e32 v6, v11, v11
	v_max_f32_e32 v0, v0, v6
	ds_bpermute_b32 v6, v10, v3
	s_waitcnt lgkmcnt(1)
	v_max_f32_e32 v9, v9, v9
	ds_bpermute_b32 v11, v10, v2
	v_max_f32_e32 v1, v1, v9
	ds_bpermute_b32 v9, v10, v4
	s_waitcnt lgkmcnt(2)
	v_max_f32_e32 v6, v6, v6
	v_max_f32_e32 v3, v3, v6
	s_waitcnt lgkmcnt(1)
	v_max_f32_e32 v6, v11, v11
	v_max_f32_e32 v2, v2, v6
	s_waitcnt lgkmcnt(0)
	v_max_f32_e32 v6, v9, v9
	ds_bpermute_b32 v9, v10, v5
	v_xor_b32_e32 v10, 8, v7
	v_cmp_lt_i32_e32 vcc, v10, v8
	v_max_f32_e32 v4, v4, v6
	s_waitcnt lgkmcnt(0)
	v_max_f32_e32 v6, v9, v9
	v_cndmask_b32_e32 v10, v7, v10, vcc
	v_lshlrev_b32_e32 v10, 2, v10
	ds_bpermute_b32 v11, v10, v0
	ds_bpermute_b32 v9, v10, v1
	v_max_f32_e32 v5, v5, v6
	s_waitcnt lgkmcnt(1)
	v_max_f32_e32 v6, v11, v11
	v_max_f32_e32 v0, v0, v6
	ds_bpermute_b32 v6, v10, v3
	s_waitcnt lgkmcnt(1)
	v_max_f32_e32 v9, v9, v9
	ds_bpermute_b32 v11, v10, v2
	v_max_f32_e32 v1, v1, v9
	ds_bpermute_b32 v9, v10, v4
	s_waitcnt lgkmcnt(2)
	v_max_f32_e32 v6, v6, v6
	v_max_f32_e32 v6, v3, v6
	s_waitcnt lgkmcnt(1)
	v_max_f32_e32 v3, v11, v11
	v_max_f32_e32 v11, v2, v3
	s_waitcnt lgkmcnt(0)
	v_max_f32_e32 v2, v9, v9
	ds_bpermute_b32 v3, v10, v5
	v_xor_b32_e32 v9, 16, v7
	v_cmp_lt_i32_e32 vcc, v9, v8
	v_max_f32_e32 v10, v4, v2
	s_waitcnt lgkmcnt(0)
	v_max_f32_e32 v2, v3, v3
	v_cndmask_b32_e32 v9, v7, v9, vcc
	v_lshlrev_b32_e32 v180, 2, v9
	ds_bpermute_b32 v9, v180, v0
	ds_bpermute_b32 v4, v180, v1
	v_max_f32_e32 v12, v5, v2
	ds_bpermute_b32 v5, v180, v6
	s_waitcnt lgkmcnt(2)
	v_max_f32_e32 v2, v9, v9
	v_max_f32_e32 v3, v0, v2
	s_waitcnt lgkmcnt(1)
	v_max_f32_e32 v0, v4, v4
	v_max_f32_e32 v2, v1, v0
	ds_bpermute_b32 v0, v180, v11
	s_waitcnt lgkmcnt(1)
	v_max_f32_e32 v1, v5, v5
	ds_bpermute_b32 v9, v180, v10
	v_max_f32_e32 v4, v6, v1
	ds_bpermute_b32 v1, v180, v12
	s_waitcnt lgkmcnt(2)
	v_max_f32_e32 v0, v0, v0
	v_max_f32_e32 v5, v11, v0
	s_waitcnt lgkmcnt(1)
	v_max_f32_e32 v0, v9, v9
	v_max_f32_e32 v0, v10, v0
	s_waitcnt lgkmcnt(0)
	v_max_f32_e32 v1, v1, v1
	v_max_f32_e32 v10, v12, v1
	v_xor_b32_e32 v1, 32, v7
	v_cmp_lt_i32_e32 vcc, v1, v8
	s_nop 1
	v_cndmask_b32_e32 v1, v7, v1, vcc
	v_lshlrev_b32_e32 v181, 2, v1
	ds_bpermute_b32 v9, v181, v3
	ds_bpermute_b32 v8, v181, v2
	ds_bpermute_b32 v7, v181, v4
	ds_bpermute_b32 v6, v181, v5
	ds_bpermute_b32 v1, v181, v0
	ds_bpermute_b32 v11, v181, v10
	v_cmp_eq_u32_e32 vcc, 0, v191
	s_and_saveexec_b64 s[0:1], vcc
	s_cbranch_execz .LBB0_271
	s_lshl_b32 s4, s3, 2
	s_add_i32 s4, s4, 0
	s_waitcnt lgkmcnt(0)
	v_max_f32_e32 v11, v11, v11
	v_max_f32_e32 v10, v10, v10
	s_add_i32 s4, s4, 0x24000
	v_max_f32_e32 v10, v10, v11
	v_mov_b32_e32 v11, s4
	ds_write_b32 v11, v10
